# scan producer: 1-(float)om through v_fma_mix_f32 (f16 source read in place) instead of v_cvt_f32_f16 + v_sub; DPP wait states re-padded
# baseline (speedup 1.0000x reference)
.LBB0_1069:
	s_waitcnt vmcnt(16)
	v_lshlrev_b32_e32 v116, 16, v72
	v_and_b32_e32 v117, 0xffff0000, v72
	s_waitcnt vmcnt(16)
	v_lshlrev_b32_e32 v104, 16, v78
	v_and_b32_e32 v105, 0xffff0000, v78
	v_pk_mul_f32 v[108:109], v[0:1], v[116:117]
	v_lshlrev_b32_e32 v72, 16, v73
	v_and_b32_e32 v73, 0xffff0000, v73
	v_pk_mul_f32 v[110:111], v[108:109], v[108:109]
	v_pk_mul_f32 v[112:113], v[2:3], v[72:73]
	s_waitcnt vmcnt(15)
	v_lshlrev_b32_e32 v118, 16, v68
	v_and_b32_e32 v119, 0xffff0000, v68
	v_pk_mul_f32 v[114:115], v[112:113], v[112:113]
	v_add_f32_e32 v68, v110, v111
	v_add_f32_e32 v68, v114, v68
	v_add_f32_e32 v68, v115, v68
	s_nop 1
	v_add_f32_dpp v68, v68, v68 quad_perm:[1,0,3,2] row_mask:0xf bank_mask:0xf bound_ctrl:1
	v_lshlrev_b32_e32 v106, 16, v79
	s_nop 0
	v_add_f32_dpp v68, v68, v68 quad_perm:[2,3,0,1] row_mask:0xf bank_mask:0xf bound_ctrl:1
	v_and_b32_e32 v107, 0xffff0000, v79
	s_nop 0
	v_add_f32_dpp v68, v68, v68 row_half_mirror row_mask:0xf bank_mask:0xf bound_ctrl:1
	v_lshlrev_b32_e32 v120, 16, v69
	s_nop 0
	v_add_f32_dpp v68, v68, v68 row_ror:8 row_mask:0xf bank_mask:0xf bound_ctrl:1
	v_max_f32_e32 v68, 0x179abe15, v68
	v_rsq_f32_e32 v68, v68
	v_and_b32_e32 v121, 0xffff0000, v69
	v_fma_mix_f32 v78, -v77, 1.0, 1.0 op_sel:[0,0,0] op_sel_hi:[1,0,0]
	v_fma_mix_f32 v79, -v77, 1.0, 1.0 op_sel:[1,0,0] op_sel_hi:[1,0,0]
	v_fma_mix_f32 v77, -v76, 1.0, 1.0 op_sel:[1,0,0] op_sel_hi:[1,0,0]
	v_fma_mix_f32 v76, -v76, 1.0, 1.0 op_sel:[0,0,0] op_sel_hi:[1,0,0]
	v_pk_mul_f32 v[108:109], v[108:109], v[68:69] op_sel_hi:[1,0]
	v_pk_mul_f32 v[110:111], v[112:113], v[68:69] op_sel_hi:[1,0]
	v_pk_mul_f32 v[112:113], v[108:109], v[118:119]
	v_pk_add_f32 v[68:69], v[120:121], -1.0 op_sel_hi:[1,0]
	v_pk_add_f32 v[118:119], v[118:119], -1.0 op_sel_hi:[1,0]
	v_pk_mul_f32 v[114:115], v[110:111], v[120:121]
	v_pk_fma_f32 v[120:121], v[4:5], v[118:119], 1.0 op_sel_hi:[1,1,0]
	v_pk_fma_f32 v[68:69], v[6:7], v[68:69], 1.0 op_sel_hi:[1,1,0]
	v_pk_mul_f32 v[116:117], v[120:121], v[116:117]
	v_pk_mul_f32 v[118:119], v[68:69], v[72:73]
	ds_write_b128 v61, v[76:79] offset:41984
	ds_write_b128 v61, v[108:111] offset:46080
	ds_write_b128 v61, v[112:115] offset:50176
	ds_write_b128 v61, v[116:119] offset:54272
	ds_write_b128 v61, v[104:107] offset:58368
	s_and_saveexec_b64 s[56:57], s[6:7]
	v_lshlrev_b32_e32 v76, 16, v24
	v_and_b32_e32 v77, 0xffff0000, v24
	v_lshlrev_b32_e32 v78, 16, v25
	v_and_b32_e32 v79, 0xffff0000, v25
	ds_write_b128 v88, v[76:79] offset:62464
	s_or_b64 exec, exec, s[56:57]
	s_waitcnt vmcnt(11)
	v_lshlrev_b32_e32 v68, 16, v26
	v_and_b32_e32 v69, 0xffff0000, v26
	v_lshlrev_b32_e32 v76, 16, v30
	v_and_b32_e32 v77, 0xffff0000, v30
	v_lshlrev_b32_e32 v78, 16, v31
	v_and_b32_e32 v79, 0xffff0000, v31
	v_lshlrev_b32_e32 v108, 16, v27
	v_and_b32_e32 v109, 0xffff0000, v27
	v_pk_mul_f32 v[24:25], v[0:1], v[68:69]
	v_pk_mul_f32 v[26:27], v[24:25], v[24:25]
	v_pk_mul_f32 v[104:105], v[2:3], v[108:109]
	v_add_f32_e32 v26, v26, v27
	v_pk_mul_f32 v[106:107], v[104:105], v[104:105]
	s_waitcnt vmcnt(10)
	v_lshlrev_b32_e32 v72, 16, v28
	v_add_f32_e32 v26, v106, v26
	v_add_f32_e32 v26, v107, v26
	v_and_b32_e32 v73, 0xffff0000, v28
	v_lshlrev_b32_e32 v28, 16, v29
	v_add_f32_dpp v26, v26, v26 quad_perm:[1,0,3,2] row_mask:0xf bank_mask:0xf bound_ctrl:1
	v_and_b32_e32 v29, 0xffff0000, v29
	v_fma_mix_f32 v30, -v32, 1.0, 1.0 op_sel:[0,0,0] op_sel_hi:[1,0,0]
	v_fma_mix_f32 v31, -v32, 1.0, 1.0 op_sel:[1,0,0] op_sel_hi:[1,0,0]
	v_fma_mix_f32 v32, -v33, 1.0, 1.0 op_sel:[0,0,0] op_sel_hi:[1,0,0]
	v_fma_mix_f32 v33, -v33, 1.0, 1.0 op_sel:[1,0,0] op_sel_hi:[1,0,0]
	v_add_f32_dpp v26, v26, v26 quad_perm:[2,3,0,1] row_mask:0xf bank_mask:0xf bound_ctrl:1
	s_nop 1
	v_add_f32_dpp v26, v26, v26 row_half_mirror row_mask:0xf bank_mask:0xf bound_ctrl:1
	s_nop 1
	v_add_f32_dpp v26, v26, v26 row_ror:8 row_mask:0xf bank_mask:0xf bound_ctrl:1
	v_max_f32_e32 v26, 0x179abe15, v26
	v_rsq_f32_e32 v26, v26
	s_nop 0
	v_pk_mul_f32 v[24:25], v[24:25], v[26:27] op_sel_hi:[1,0]
	v_pk_mul_f32 v[26:27], v[104:105], v[26:27] op_sel_hi:[1,0]
	v_pk_mul_f32 v[104:105], v[24:25], v[72:73]
	v_pk_mul_f32 v[106:107], v[26:27], v[28:29]
	v_pk_add_f32 v[28:29], v[28:29], -1.0 op_sel_hi:[1,0]
	v_pk_add_f32 v[72:73], v[72:73], -1.0 op_sel_hi:[1,0]
	v_pk_fma_f32 v[28:29], v[6:7], v[28:29], 1.0 op_sel_hi:[1,1,0]
	v_pk_fma_f32 v[72:73], v[4:5], v[72:73], 1.0 op_sel_hi:[1,1,0]
	v_pk_mul_f32 v[110:111], v[28:29], v[108:109]
	v_pk_mul_f32 v[108:109], v[72:73], v[68:69]
	ds_write_b128 v61, v[30:33] offset:62976
	ds_write_b128 v89, v[24:27]
	ds_write_b128 v90, v[104:107]
	ds_write_b128 v91, v[108:111]
	ds_write_b128 v92, v[76:79]
	s_and_saveexec_b64 s[56:57], s[6:7]
	v_lshlrev_b32_e32 v24, 16, v20
	v_and_b32_e32 v25, 0xffff0000, v20
	v_lshlrev_b32_e32 v26, 16, v21
	v_and_b32_e32 v27, 0xffff0000, v21
	ds_write_b128 v97, v[24:27] offset:20480
	s_or_b64 exec, exec, s[56:57]
	ds_read_b128 v[24:27], v94
	ds_read_b128 v[28:31], v94 offset:16
	ds_read_b128 v[76:79], v94 offset:32
	ds_read_b128 v[104:107], v94 offset:48
	s_waitcnt lgkmcnt(0)
	v_pk_add_f32 v[24:25], v[24:25], v[26:27]
	v_pk_add_f32 v[28:29], v[28:29], v[30:31]
	v_pk_add_f32 v[76:77], v[76:77], v[78:79]
	v_pk_add_f32 v[104:105], v[104:105], v[106:107]
	v_pk_add_f32 v[24:25], v[24:25], v[28:29]
	v_pk_add_f32 v[76:77], v[76:77], v[104:105]
	s_min_u32 s56, s52, 1
	s_lshl_b32 s56, s56, 4
	s_add_i32 s61, s61, 2
	s_waitcnt vmcnt(6)
	v_pk_add_f32 v[24:25], v[24:25], v[76:77]
	s_nop 0
	v_add_f32_e32 v20, v24, v25
	v_lshlrev_b32_e32 v104, 16, v86
	v_add_u32_e32 v24, s56, v9
	v_subrev_u32_e32 v21, s56, v17
	v_cndmask_b32_e64 v134, v24, v21, s[4:5]
	v_fma_mixlo_f16 v24, v20, s82, 0
	v_lshl_add_u64 v[20:21], v[10:11], 0, v[134:135]
	v_lshlrev_b64 v[20:21], 10, v[20:21]
	s_min_u32 s56, s61, 0x1fc
	v_lshl_add_u64 v[20:21], v[12:13], 0, v[20:21]
	v_lshl_add_u32 v134, s56, 4, v95
	global_store_short v[20:21], v24, off
	v_lshl_add_u64 v[20:21], s[54:55], 0, v[134:135]
	v_mad_u64_u32 v[26:27], s[56:57], v20, s50, v[18:19]
	v_mad_i32_i24 v27, v21, s50, v27
	v_lshlrev_b64 v[20:21], 10, v[20:21]
	v_lshl_add_u64 v[24:25], v[14:15], 0, v[20:21]
	v_or_b32_e32 v20, v20, v103
	v_lshlrev_b64 v[20:21], 1, v[20:21]
	v_lshl_add_u64 v[28:29], v[42:43], 0, v[20:21]
	v_lshl_add_u64 v[20:21], v[44:45], 0, v[20:21]
	global_load_dwordx2 v[76:77], v[20:21], off
	v_sub_u32_e32 v20, 0x1fff, v134
	v_or_b32_e32 v20, s54, v20
	global_load_dwordx2 v[68:69], v[28:29], off
	v_mad_u64_u32 v[28:29], s[56:57], v20, s50, v[18:19]
	v_mov_b32_e32 v21, s55
	v_mad_i32_i24 v29, s55, v166, v29
	global_load_dwordx2 v[24:25], v[24:25], off
	s_nop 0
	global_load_dwordx2 v[78:79], v[26:27], off offset:1024
	global_load_dwordx2 v[72:73], v[26:27], off offset:2048
	global_load_dwordx2 v[30:31], v[28:29], off offset:1024
	s_nop 0
	global_load_dwordx2 v[26:27], v[28:29], off offset:2048
	v_lshlrev_b64 v[28:29], 10, v[20:21]
	v_lshl_add_u64 v[20:21], v[14:15], 0, v[28:29]
	v_or_b32_e32 v28, v28, v16
	v_lshlrev_b64 v[32:33], 1, v[28:29]
	v_lshl_add_u64 v[28:29], v[42:43], 0, v[32:33]
	v_lshl_add_u64 v[32:33], v[44:45], 0, v[32:33]
	global_load_dwordx2 v[20:21], v[20:21], off
	v_and_b32_e32 v105, 0xffff0000, v86
	global_load_dwordx2 v[28:29], v[28:29], off
	v_lshlrev_b32_e32 v106, 16, v87
	global_load_dwordx2 v[32:33], v[32:33], off
	v_and_b32_e32 v107, 0xffff0000, v87
	s_waitcnt vmcnt(17)
	s_waitcnt vmcnt(16)
	v_lshlrev_b32_e32 v86, 16, v82
	v_and_b32_e32 v87, 0xffff0000, v82
	v_lshlrev_b32_e32 v118, 16, v83
	v_and_b32_e32 v119, 0xffff0000, v83
	v_pk_mul_f32 v[108:109], v[0:1], v[86:87]
	v_pk_mul_f32 v[112:113], v[2:3], v[118:119]
	v_pk_mul_f32 v[110:111], v[108:109], v[108:109]
	s_waitcnt vmcnt(16)
	v_lshlrev_b32_e32 v116, 16, v80
	v_and_b32_e32 v117, 0xffff0000, v80
	v_pk_mul_f32 v[114:115], v[112:113], v[112:113]
	v_add_f32_e32 v80, v110, v111
	v_add_f32_e32 v80, v114, v80
	v_add_f32_e32 v80, v115, v80
	s_waitcnt lgkmcnt(0)
	s_barrier
	v_add_f32_dpp v80, v80, v80 quad_perm:[1,0,3,2] row_mask:0xf bank_mask:0xf bound_ctrl:1
	v_lshlrev_b32_e32 v120, 16, v81
	v_and_b32_e32 v121, 0xffff0000, v81
	v_add_f32_dpp v80, v80, v80 quad_perm:[2,3,0,1] row_mask:0xf bank_mask:0xf bound_ctrl:1
	v_fma_mix_f32 v82, -v84, 1.0, 1.0 op_sel:[0,0,0] op_sel_hi:[1,0,0]
	v_fma_mix_f32 v83, -v84, 1.0, 1.0 op_sel:[1,0,0] op_sel_hi:[1,0,0]
	v_fma_mix_f32 v84, -v85, 1.0, 1.0 op_sel:[0,0,0] op_sel_hi:[1,0,0]
	v_fma_mix_f32 v85, -v85, 1.0, 1.0 op_sel:[1,0,0] op_sel_hi:[1,0,0]
	s_nop 0
	v_add_f32_dpp v80, v80, v80 row_half_mirror row_mask:0xf bank_mask:0xf bound_ctrl:1
	s_nop 1
	v_add_f32_dpp v80, v80, v80 row_ror:8 row_mask:0xf bank_mask:0xf bound_ctrl:1
	v_max_f32_e32 v80, 0x179abe15, v80
	v_rsq_f32_e32 v80, v80
	s_nop 0
	v_pk_mul_f32 v[108:109], v[108:109], v[80:81] op_sel_hi:[1,0]
	v_pk_mul_f32 v[110:111], v[112:113], v[80:81] op_sel_hi:[1,0]
	v_pk_mul_f32 v[112:113], v[108:109], v[116:117]
	v_pk_add_f32 v[80:81], v[120:121], -1.0 op_sel_hi:[1,0]
	v_pk_add_f32 v[116:117], v[116:117], -1.0 op_sel_hi:[1,0]
	v_pk_fma_f32 v[80:81], v[6:7], v[80:81], 1.0 op_sel_hi:[1,1,0]
	v_pk_fma_f32 v[116:117], v[4:5], v[116:117], 1.0 op_sel_hi:[1,1,0]
	v_pk_mul_f32 v[114:115], v[110:111], v[120:121]
	v_pk_mul_f32 v[118:119], v[80:81], v[118:119]
	v_pk_mul_f32 v[116:117], v[116:117], v[86:87]
	ds_write_b128 v61, v[82:85]
	ds_write_b128 v61, v[108:111] offset:4096
	ds_write_b128 v61, v[112:115] offset:8192
	ds_write_b128 v61, v[116:119] offset:12288
	ds_write_b128 v61, v[104:107] offset:16384
	s_and_saveexec_b64 s[56:57], s[6:7]
	v_lshlrev_b32_e32 v80, 16, v34
	v_and_b32_e32 v81, 0xffff0000, v34
	v_lshlrev_b32_e32 v82, 16, v35
	v_and_b32_e32 v83, 0xffff0000, v35
	ds_write_b128 v88, v[80:83] offset:20480
	s_or_b64 exec, exec, s[56:57]
	s_waitcnt vmcnt(11)
	v_lshlrev_b32_e32 v80, 16, v70
	v_and_b32_e32 v81, 0xffff0000, v70
	v_lshlrev_b32_e32 v82, 16, v71
	v_and_b32_e32 v83, 0xffff0000, v71
	v_lshlrev_b32_e32 v70, 16, v36
	v_and_b32_e32 v71, 0xffff0000, v36
	v_lshlrev_b32_e32 v108, 16, v37
	v_and_b32_e32 v109, 0xffff0000, v37
	v_pk_mul_f32 v[34:35], v[0:1], v[70:71]
	v_pk_mul_f32 v[36:37], v[34:35], v[34:35]
	v_pk_mul_f32 v[104:105], v[2:3], v[108:109]
	v_add_f32_e32 v36, v36, v37
	v_pk_mul_f32 v[106:107], v[104:105], v[104:105]
	v_add_f32_e32 v36, v106, v36
	v_add_f32_e32 v36, v107, v36
	v_fma_mix_f32 v86, -v75, 1.0, 1.0 op_sel:[0,0,0] op_sel_hi:[1,0,0]
	v_fma_mix_f32 v84, -v74, 1.0, 1.0 op_sel:[0,0,0] op_sel_hi:[1,0,0]
	v_fma_mix_f32 v87, -v75, 1.0, 1.0 op_sel:[1,0,0] op_sel_hi:[1,0,0]
	v_fma_mix_f32 v85, -v74, 1.0, 1.0 op_sel:[1,0,0] op_sel_hi:[1,0,0]
	v_lshlrev_b32_e32 v74, 16, v38
	v_and_b32_e32 v75, 0xffff0000, v38
	v_add_f32_dpp v36, v36, v36 quad_perm:[1,0,3,2] row_mask:0xf bank_mask:0xf bound_ctrl:1
	v_lshlrev_b32_e32 v38, 16, v39
	v_and_b32_e32 v39, 0xffff0000, v39
	v_add_f32_dpp v36, v36, v36 quad_perm:[2,3,0,1] row_mask:0xf bank_mask:0xf bound_ctrl:1
	s_nop 0
	s_nop 0
	v_add_f32_dpp v36, v36, v36 row_half_mirror row_mask:0xf bank_mask:0xf bound_ctrl:1
	s_nop 1
	v_add_f32_dpp v36, v36, v36 row_ror:8 row_mask:0xf bank_mask:0xf bound_ctrl:1
	v_max_f32_e32 v36, 0x179abe15, v36
	v_rsq_f32_e32 v36, v36
	s_nop 0
	v_pk_mul_f32 v[34:35], v[34:35], v[36:37] op_sel_hi:[1,0]
	v_pk_mul_f32 v[36:37], v[104:105], v[36:37] op_sel_hi:[1,0]
	v_pk_mul_f32 v[104:105], v[34:35], v[74:75]
	v_pk_mul_f32 v[106:107], v[36:37], v[38:39]
	v_pk_add_f32 v[38:39], v[38:39], -1.0 op_sel_hi:[1,0]
	v_pk_add_f32 v[74:75], v[74:75], -1.0 op_sel_hi:[1,0]
	v_pk_fma_f32 v[38:39], v[6:7], v[38:39], 1.0 op_sel_hi:[1,1,0]
	v_pk_fma_f32 v[74:75], v[4:5], v[74:75], 1.0 op_sel_hi:[1,1,0]
	v_pk_mul_f32 v[110:111], v[38:39], v[108:109]
	v_pk_mul_f32 v[108:109], v[74:75], v[70:71]
	ds_write_b128 v61, v[84:87] offset:20992
	ds_write_b128 v61, v[34:37] offset:25088
	ds_write_b128 v61, v[104:107] offset:29184
	ds_write_b128 v61, v[108:111] offset:33280
	ds_write_b128 v61, v[80:83] offset:37376
	s_and_saveexec_b64 s[56:57], s[6:7]
	s_cbranch_execz .LBB0_1068
	v_lshlrev_b32_e32 v34, 16, v22
	v_and_b32_e32 v35, 0xffff0000, v22
	v_lshlrev_b32_e32 v36, 16, v23
	v_and_b32_e32 v37, 0xffff0000, v23
	ds_write_b128 v88, v[34:37] offset:41472
	s_branch .LBB0_1068
